# weight-conversion hook between attention units: all 32 source loads of an item requested before the conversion starts (one memory round instead of two)
# speedup vs baseline: 1.0073x; 1.0010x over previous
.LBB0_389:
	s_nop 1
	v_mov_b32_e32 v0, v213
	s_waitcnt lgkmcnt(0)
	s_barrier
	s_cmp_eq_u32 s57, 7
	v_mbcnt_lo_u32_b32 v0, -1, v0
	v_mbcnt_hi_u32_b32 v0, -1, v0
	v_add_u32_e32 v88, s58, v0
	s_mov_b64 s[2:3], -1
	v_and_b32_e32 v89, 63, v88
	s_cbranch_scc1 .LBB0_431
	s_mul_i32 s14, s57, s81
	v_readlane_b32 s2, v254, 3
	s_add_i32 s2, s14, s2
	s_cmpk_gt_i32 s2, 0x2fff
	s_cbranch_scc1 .LBB0_430
	s_mov_b64 s[2:3], s[0:1]
	s_load_dwordx2 s[2:3], s[2:3], 0x98
	s_add_i32 s14, s14, s73
	s_cmpk_gt_i32 s14, 0x1fff
	s_mov_b64 s[4:5], -1
	s_cbranch_scc0 .LBB0_395
	s_cmpk_gt_u32 s14, 0x2fff
	s_cbranch_scc1 .LBB0_394
	s_add_i32 s4, s14, 0xffffe000
	s_lshr_b32 s38, s4, 7
	s_mov_b64 s[4:5], s[0:1]
	s_load_dwordx2 s[4:5], s[4:5], 0x80
	s_and_b32 s24, s14, 0x7f
	s_lshl_b64 s[20:21], s[38:39], 20
	s_add_u32 s20, s20, s29
	s_addc_u32 s21, s21, 0
	s_lshl_b64 s[22:23], s[20:21], 2
	s_waitcnt lgkmcnt(0)
	s_add_u32 s25, s4, s22
	s_addc_u32 s26, s5, s23
	s_add_u32 s15, s2, s20
	s_addc_u32 s20, s3, s21
	s_bfe_u32 s27, s14, 0x30004
	s_lshl_b32 s4, s27, 10
	s_lshl_b32 s5, s24, 6
	s_sub_i32 s4, s5, s4
	s_ashr_i32 s5, s4, 31
	s_lshl_b32 s21, s27, 7
	s_lshl_b64 s[22:23], s[4:5], 2
	s_add_u32 s22, s25, s22
	v_lshlrev_b32_e32 v0, 4, v89
	v_lshrrev_b32_e32 v130, 4, v89
	s_addc_u32 s23, s26, s23
	v_and_b32_e32 v212, 0xf0, v0
	s_lshl_b32 s5, s27, 19
	v_lshl_add_u64 v[0:1], s[22:23], 0, v[212:213]
	v_lshl_or_b32 v2, v130, 14, s5
	v_mov_b32_e32 v3, v213
	v_lshl_add_u64 v[8:9], v[0:1], 0, v[2:3]
	v_add_co_u32_e32 v0, vcc, s35, v8
	s_movk_i32 s5, 0x3000
	s_nop 0
	v_addc_co_u32_e32 v1, vcc, 0, v9, vcc
	global_load_dwordx4 v[48:51], v[0:1], off offset:-4096 nt
	global_load_dwordx4 v[52:55], v[0:1], off nt
	v_add_co_u32_e32 v0, vcc, s5, v8
	s_mov_b32 s5, 0x41000
	s_nop 1
	v_addc_co_u32_e32 v1, vcc, 0, v9, vcc
	global_load_dwordx4 v[56:59], v[8:9], off nt
	global_load_dwordx4 v[60:63], v[0:1], off nt
	v_add_co_u32_e32 v0, vcc, s68, v8
	s_nop 1
	v_addc_co_u32_e32 v1, vcc, 0, v9, vcc
	global_load_dwordx4 v[64:67], v[0:1], off offset:-4096 nt
	global_load_dwordx4 v[68:71], v[0:1], off nt
	v_add_co_u32_e32 v0, vcc, s69, v8
	s_nop 1
	v_addc_co_u32_e32 v1, vcc, 0, v9, vcc
	global_load_dwordx4 v[72:75], v[0:1], off offset:-4096 nt
	global_load_dwordx4 v[76:79], v[0:1], off nt
	v_add_co_u32_e32 v0, vcc, s30, v8
	s_nop 1
	v_addc_co_u32_e32 v1, vcc, 0, v9, vcc
	global_load_dwordx4 v[80:83], v[0:1], off offset:-4096 nt
	global_load_dwordx4 v[84:87], v[0:1], off nt
	v_add_co_u32_e32 v0, vcc, s34, v8
	s_nop 1
	v_addc_co_u32_e32 v1, vcc, 0, v9, vcc
	global_load_dwordx4 v[90:93], v[0:1], off offset:-4096 nt
	global_load_dwordx4 v[94:97], v[0:1], off nt
	v_add_co_u32_e32 v0, vcc, s67, v8
	s_nop 1
	v_addc_co_u32_e32 v1, vcc, 0, v9, vcc
	global_load_dwordx4 v[98:101], v[0:1], off offset:-4096 nt
	global_load_dwordx4 v[102:105], v[0:1], off nt
	v_add_co_u32_e32 v0, vcc, s70, v8
	s_nop 1
	v_addc_co_u32_e32 v1, vcc, 0, v9, vcc
	global_load_dwordx4 v[106:109], v[0:1], off offset:-4096 nt
	global_load_dwordx4 v[110:113], v[0:1], off nt
	v_add_co_u32_e32 v0, vcc, s5, v8
	s_mov_b32 s5, 0x43000
	s_nop 1
	v_addc_co_u32_e32 v1, vcc, 0, v9, vcc
	global_load_dwordx4 v[114:117], v[0:1], off offset:-4096 nt
	global_load_dwordx4 v[118:121], v[0:1], off nt
	v_add_co_u32_e32 v0, vcc, s5, v8
	s_mov_b32 s5, 0x51000
	s_nop 1
	v_addc_co_u32_e32 v1, vcc, 0, v9, vcc
	global_load_dwordx4 v[122:125], v[0:1], off offset:-4096 nt
	global_load_dwordx4 v[126:129], v[0:1], off nt
	v_add_co_u32_e32 v0, vcc, s5, v8
	s_mov_b32 s5, 0x53000
	s_nop 1
	v_addc_co_u32_e32 v1, vcc, 0, v9, vcc
	global_load_dwordx4 v[32:35], v[0:1], off offset:-4096 nt
	global_load_dwordx4 v[36:39], v[0:1], off nt
	v_add_co_u32_e32 v0, vcc, s5, v8
	s_nop 1
	v_addc_co_u32_e32 v1, vcc, 0, v9, vcc
	global_load_dwordx4 v[40:43], v[0:1], off offset:-4096 nt
	global_load_dwordx4 v[44:47], v[0:1], off nt
	s_mov_b32 s5, 0x61000
	v_add_co_u32_e32 v0, vcc, s5, v8
	s_nop 1
	v_addc_co_u32_e32 v1, vcc, 0, v9, vcc
	s_mov_b32 s5, 0x63000
	global_load_dwordx4 v[16:19], v[0:1], off offset:-4096 nt
	global_load_dwordx4 v[20:23], v[0:1], off nt
	v_add_co_u32_e32 v0, vcc, s5, v8
	s_mov_b32 s5, 0x71000
	s_nop 1
	v_addc_co_u32_e32 v1, vcc, 0, v9, vcc
	v_add_co_u32_e32 v4, vcc, s5, v8
	s_nop 1
	v_addc_co_u32_e32 v5, vcc, 0, v9, vcc
	s_mov_b32 s5, 0x73000
	v_add_co_u32_e32 v12, vcc, s5, v8
	s_nop 1
	v_addc_co_u32_e32 v13, vcc, 0, v9, vcc
	global_load_dwordx4 v[24:27], v[0:1], off offset:-4096 nt
	global_load_dwordx4 v[28:31], v[0:1], off nt
	global_load_dwordx4 v[0:3], v[4:5], off offset:-4096 nt
	global_load_dwordx4 v[4:7], v[4:5], off nt
	global_load_dwordx4 v[8:11], v[12:13], off offset:-4096 nt
	global_load_dwordx4 v[12:15], v[12:13], off nt
	s_nop 0
	v_mov_b32_e32 v131, v213
	s_nop 0
	s_add_u32 s22, s15, s21
	s_nop 0
	s_addc_u32 s23, s20, 0
	s_nop 0
	s_mov_b64 s[20:21], 0x24000000
	s_nop 0
	s_waitcnt vmcnt(31)
	v_mul_f32_e32 v48, 0x42800000, v48
	s_waitcnt vmcnt(29)
	v_mul_f32_e32 v56, 0x42800000, v56
	s_nop 0
	s_nop 0
	s_nop 0
	v_cvt_pk_fp8_f32 v131, v56, v48
	s_nop 0
	v_mul_f32_e32 v56, 0x42800000, v57
	v_mul_f32_e32 v49, 0x42800000, v49
	v_mov_b32_e32 v57, v213
	v_cvt_pk_fp8_f32 v57, v56, v49
	v_mul_f32_e32 v48, 0x42800000, v52
	s_waitcnt vmcnt(28)
	v_mul_f32_e32 v52, 0x42800000, v60
	v_cvt_pk_fp8_f32 v131, v48, v52 op_sel:[0,0,1]
	v_mul_f32_e32 v48, 0x42800000, v53
	v_mul_f32_e32 v49, 0x42800000, v61
	v_cvt_pk_fp8_f32 v57, v48, v49 op_sel:[0,0,1]
	v_mul_f32_e32 v48, 0x42800000, v58
	v_mul_f32_e32 v49, 0x42800000, v50
	v_mov_b32_e32 v50, v213
	v_cvt_pk_fp8_f32 v50, v48, v49
	v_mul_f32_e32 v52, 0x42800000, v59
	v_mul_f32_e32 v51, 0x42800000, v51
	v_mov_b32_e32 v53, v213
	v_cvt_pk_fp8_f32 v53, v52, v51
	s_nop 0
	v_mul_f32_e32 v48, 0x42800000, v54
	v_mul_f32_e32 v49, 0x42800000, v62
	v_cvt_pk_fp8_f32 v50, v48, v49 op_sel:[0,0,1]
	v_mul_f32_e32 v48, 0x42800000, v55
	v_mul_f32_e32 v49, 0x42800000, v63
	v_cvt_pk_fp8_f32 v53, v48, v49 op_sel:[0,0,1]
	v_mul_u32_u24_e32 v48, 0x104, v130
	s_nop 0
	v_add3_u32 v48, s89, v212, v48
	s_nop 0
	s_nop 0
	s_nop 0
	s_nop 0
	ds_write2_b32 v48, v131, v57 offset1:1
	ds_write2_b32 v48, v50, v53 offset0:2 offset1:3
	s_waitcnt vmcnt(27)
	v_mul_f32_e32 v49, 0x42800000, v64
	s_waitcnt vmcnt(26)
	v_mul_f32_e32 v50, 0x42800000, v68
	v_mov_b32_e32 v51, v213
	v_cvt_pk_fp8_f32 v51, v49, v50
	v_mul_f32_e32 v52, 0x42800000, v65
	v_mul_f32_e32 v53, 0x42800000, v69
	v_mov_b32_e32 v54, v213
	v_cvt_pk_fp8_f32 v54, v52, v53
	s_waitcnt vmcnt(25)
	v_mul_f32_e32 v49, 0x42800000, v72
	s_waitcnt vmcnt(24)
	v_mul_f32_e32 v50, 0x42800000, v76
	v_cvt_pk_fp8_f32 v51, v49, v50 op_sel:[0,0,1]
	v_mul_f32_e32 v49, 0x42800000, v73
	v_mul_f32_e32 v50, 0x42800000, v77
	v_cvt_pk_fp8_f32 v54, v49, v50 op_sel:[0,0,1]
	v_mul_f32_e32 v49, 0x42800000, v66
	v_mul_f32_e32 v50, 0x42800000, v70
	v_mov_b32_e32 v52, v213
	v_cvt_pk_fp8_f32 v52, v49, v50
	v_mul_f32_e32 v53, 0x42800000, v67
	v_mul_f32_e32 v55, 0x42800000, v71
	v_mov_b32_e32 v56, v213
	v_cvt_pk_fp8_f32 v56, v53, v55
	v_mul_f32_e32 v49, 0x42800000, v74
	v_mul_f32_e32 v50, 0x42800000, v78
	v_cvt_pk_fp8_f32 v52, v49, v50 op_sel:[0,0,1]
	v_mul_f32_e32 v49, 0x42800000, v75
	v_mul_f32_e32 v50, 0x42800000, v79
	v_cvt_pk_fp8_f32 v56, v49, v50 op_sel:[0,0,1]
	v_add_u32_e32 v49, 0x410, v48
	ds_write2_b32 v49, v51, v54 offset1:1
	v_add_u32_e32 v49, 0x418, v48
	ds_write2_b32 v49, v52, v56 offset1:1
	s_waitcnt vmcnt(23)
	v_mul_f32_e32 v49, 0x42800000, v80
	s_waitcnt vmcnt(22)
	v_mul_f32_e32 v50, 0x42800000, v84
	v_mov_b32_e32 v51, v213
	v_cvt_pk_fp8_f32 v51, v49, v50
	v_mul_f32_e32 v52, 0x42800000, v81
	v_mul_f32_e32 v53, 0x42800000, v85
	v_mov_b32_e32 v54, v213
	v_cvt_pk_fp8_f32 v54, v52, v53
	s_waitcnt vmcnt(21)
	v_mul_f32_e32 v49, 0x42800000, v90
	s_waitcnt vmcnt(20)
	v_mul_f32_e32 v50, 0x42800000, v94
	v_cvt_pk_fp8_f32 v51, v49, v50 op_sel:[0,0,1]
	v_mul_f32_e32 v49, 0x42800000, v91
	v_mul_f32_e32 v50, 0x42800000, v95
	v_cvt_pk_fp8_f32 v54, v49, v50 op_sel:[0,0,1]
	v_mul_f32_e32 v49, 0x42800000, v82
	v_mul_f32_e32 v50, 0x42800000, v86
	v_mov_b32_e32 v52, v213
	v_cvt_pk_fp8_f32 v52, v49, v50
	v_mul_f32_e32 v53, 0x42800000, v83
	v_mul_f32_e32 v55, 0x42800000, v87
	v_mov_b32_e32 v56, v213
	v_cvt_pk_fp8_f32 v56, v53, v55
	v_mul_f32_e32 v49, 0x42800000, v92
	v_mul_f32_e32 v50, 0x42800000, v96
	v_cvt_pk_fp8_f32 v52, v49, v50 op_sel:[0,0,1]
	v_mul_f32_e32 v49, 0x42800000, v93
	v_mul_f32_e32 v50, 0x42800000, v97
	v_cvt_pk_fp8_f32 v56, v49, v50 op_sel:[0,0,1]
	v_add_u32_e32 v49, 0x820, v48
	ds_write2_b32 v49, v51, v54 offset1:1
	v_add_u32_e32 v49, 0x828, v48
	ds_write2_b32 v49, v52, v56 offset1:1
	s_waitcnt vmcnt(19)
	v_mul_f32_e32 v49, 0x42800000, v98
	s_waitcnt vmcnt(18)
	v_mul_f32_e32 v50, 0x42800000, v102
	v_mov_b32_e32 v51, v213
	v_cvt_pk_fp8_f32 v51, v49, v50
	v_mul_f32_e32 v52, 0x42800000, v99
	v_mul_f32_e32 v53, 0x42800000, v103
	v_mov_b32_e32 v54, v213
	v_cvt_pk_fp8_f32 v54, v52, v53
	s_waitcnt vmcnt(17)
	v_mul_f32_e32 v49, 0x42800000, v106
	s_waitcnt vmcnt(16)
	v_mul_f32_e32 v50, 0x42800000, v110
	v_cvt_pk_fp8_f32 v51, v49, v50 op_sel:[0,0,1]
	v_mul_f32_e32 v49, 0x42800000, v107
	v_mul_f32_e32 v50, 0x42800000, v111
	v_cvt_pk_fp8_f32 v54, v49, v50 op_sel:[0,0,1]
	v_mul_f32_e32 v49, 0x42800000, v100
	v_mul_f32_e32 v50, 0x42800000, v104
	v_mov_b32_e32 v52, v213
	v_cvt_pk_fp8_f32 v52, v49, v50
	v_mul_f32_e32 v53, 0x42800000, v101
	v_mul_f32_e32 v55, 0x42800000, v105
	v_mov_b32_e32 v56, v213
	v_cvt_pk_fp8_f32 v56, v53, v55
	v_mul_f32_e32 v49, 0x42800000, v108
	v_mul_f32_e32 v50, 0x42800000, v112
	v_cvt_pk_fp8_f32 v52, v49, v50 op_sel:[0,0,1]
	v_mul_f32_e32 v49, 0x42800000, v109
	v_mul_f32_e32 v50, 0x42800000, v113
	v_cvt_pk_fp8_f32 v56, v49, v50 op_sel:[0,0,1]
	v_add_u32_e32 v49, 0xc30, v48
	ds_write2_b32 v49, v51, v54 offset1:1
	v_add_u32_e32 v49, 0xc38, v48
	ds_write2_b32 v49, v52, v56 offset1:1
	s_waitcnt vmcnt(15)
	v_mul_f32_e32 v49, 0x42800000, v114
	s_waitcnt vmcnt(14)
	v_mul_f32_e32 v50, 0x42800000, v118
	v_mov_b32_e32 v51, v213
	v_cvt_pk_fp8_f32 v51, v49, v50
	v_mul_f32_e32 v52, 0x42800000, v115
	v_mul_f32_e32 v53, 0x42800000, v119
	v_mov_b32_e32 v54, v213
	v_cvt_pk_fp8_f32 v54, v52, v53
	s_waitcnt vmcnt(13)
	v_mul_f32_e32 v49, 0x42800000, v122
	s_waitcnt vmcnt(12)
	v_mul_f32_e32 v50, 0x42800000, v126
	v_cvt_pk_fp8_f32 v51, v49, v50 op_sel:[0,0,1]
	v_mul_f32_e32 v49, 0x42800000, v123
	v_mul_f32_e32 v50, 0x42800000, v127
	v_cvt_pk_fp8_f32 v54, v49, v50 op_sel:[0,0,1]
	v_mul_f32_e32 v49, 0x42800000, v116
	v_mul_f32_e32 v50, 0x42800000, v120
	v_mov_b32_e32 v52, v213
	v_cvt_pk_fp8_f32 v52, v49, v50
	v_mul_f32_e32 v53, 0x42800000, v117
	v_mul_f32_e32 v55, 0x42800000, v121
	v_mov_b32_e32 v56, v213
	v_cvt_pk_fp8_f32 v56, v53, v55
	v_mul_f32_e32 v49, 0x42800000, v124
	v_mul_f32_e32 v50, 0x42800000, v128
	v_cvt_pk_fp8_f32 v52, v49, v50 op_sel:[0,0,1]
	v_mul_f32_e32 v49, 0x42800000, v125
	v_mul_f32_e32 v50, 0x42800000, v129
	v_cvt_pk_fp8_f32 v56, v49, v50 op_sel:[0,0,1]
	v_add_u32_e32 v49, 0x1040, v48
	ds_write2_b32 v49, v51, v54 offset1:1
	v_add_u32_e32 v49, 0x1048, v48
	ds_write2_b32 v49, v52, v56 offset1:1
	s_waitcnt vmcnt(11)
	v_mul_f32_e32 v32, 0x42800000, v32
	s_waitcnt vmcnt(10)
	v_mul_f32_e32 v36, 0x42800000, v36
	v_mov_b32_e32 v49, v213
	v_cvt_pk_fp8_f32 v49, v32, v36
	s_waitcnt vmcnt(9)
	v_mul_f32_e32 v32, 0x42800000, v40
	v_mul_f32_e32 v33, 0x42800000, v33
	v_mul_f32_e32 v37, 0x42800000, v37
	v_mov_b32_e32 v40, v213
	v_cvt_pk_fp8_f32 v40, v33, v37
	s_waitcnt vmcnt(8)
	v_mul_f32_e32 v36, 0x42800000, v44
	v_cvt_pk_fp8_f32 v49, v32, v36 op_sel:[0,0,1]
	v_mul_f32_e32 v32, 0x42800000, v41
	v_mul_f32_e32 v33, 0x42800000, v45
	v_cvt_pk_fp8_f32 v40, v32, v33 op_sel:[0,0,1]
	v_mul_f32_e32 v32, 0x42800000, v34
	v_mul_f32_e32 v33, 0x42800000, v38
	v_mov_b32_e32 v34, v213
	v_cvt_pk_fp8_f32 v34, v32, v33
	v_mul_f32_e32 v35, 0x42800000, v35
	v_mul_f32_e32 v36, 0x42800000, v39
	v_mov_b32_e32 v37, v213
	v_cvt_pk_fp8_f32 v37, v35, v36
	v_mul_f32_e32 v32, 0x42800000, v42
	v_mul_f32_e32 v33, 0x42800000, v46
	v_cvt_pk_fp8_f32 v34, v32, v33 op_sel:[0,0,1]
	v_mul_f32_e32 v32, 0x42800000, v43
	v_mul_f32_e32 v33, 0x42800000, v47
	v_cvt_pk_fp8_f32 v37, v32, v33 op_sel:[0,0,1]
	v_add_u32_e32 v32, 0x1450, v48
	ds_write2_b32 v32, v49, v40 offset1:1
	v_add_u32_e32 v32, 0x1458, v48
	ds_write2_b32 v32, v34, v37 offset1:1
	s_waitcnt vmcnt(7)
	v_mul_f32_e32 v16, 0x42800000, v16
	s_waitcnt vmcnt(6)
	v_mul_f32_e32 v20, 0x42800000, v20
	v_mov_b32_e32 v32, v213
	v_cvt_pk_fp8_f32 v32, v16, v20
	s_waitcnt vmcnt(5)
	v_mul_f32_e32 v16, 0x42800000, v24
	v_mul_f32_e32 v17, 0x42800000, v17
	v_mul_f32_e32 v21, 0x42800000, v21
	v_mov_b32_e32 v24, v213
	v_cvt_pk_fp8_f32 v24, v17, v21
	s_waitcnt vmcnt(4)
	v_mul_f32_e32 v20, 0x42800000, v28
	v_cvt_pk_fp8_f32 v32, v16, v20 op_sel:[0,0,1]
	v_mul_f32_e32 v16, 0x42800000, v25
	v_mul_f32_e32 v17, 0x42800000, v29
	v_cvt_pk_fp8_f32 v24, v16, v17 op_sel:[0,0,1]
	v_mul_f32_e32 v16, 0x42800000, v18
	v_mul_f32_e32 v17, 0x42800000, v22
	v_mov_b32_e32 v18, v213
	v_cvt_pk_fp8_f32 v18, v16, v17
	v_mul_f32_e32 v19, 0x42800000, v19
	v_mul_f32_e32 v20, 0x42800000, v23
	v_mov_b32_e32 v21, v213
	v_cvt_pk_fp8_f32 v21, v19, v20
	v_mul_f32_e32 v16, 0x42800000, v26
	v_mul_f32_e32 v17, 0x42800000, v30
	v_cvt_pk_fp8_f32 v18, v16, v17 op_sel:[0,0,1]
	v_mul_f32_e32 v16, 0x42800000, v27
	v_mul_f32_e32 v17, 0x42800000, v31
	v_cvt_pk_fp8_f32 v21, v16, v17 op_sel:[0,0,1]
	v_add_u32_e32 v16, 0x1860, v48
	ds_write2_b32 v16, v32, v24 offset1:1
	v_add_u32_e32 v16, 0x1868, v48
	ds_write2_b32 v16, v18, v21 offset1:1
	s_waitcnt vmcnt(3)
	v_mul_f32_e32 v0, 0x42800000, v0
	s_waitcnt vmcnt(2)
	v_mul_f32_e32 v4, 0x42800000, v4
	v_mov_b32_e32 v16, v213
	v_cvt_pk_fp8_f32 v16, v0, v4
	s_waitcnt vmcnt(1)
	v_mul_f32_e32 v0, 0x42800000, v8
	v_mul_f32_e32 v1, 0x42800000, v1
	v_mul_f32_e32 v5, 0x42800000, v5
	v_mov_b32_e32 v8, v213
	v_cvt_pk_fp8_f32 v8, v1, v5
	s_waitcnt vmcnt(0)
	v_mul_f32_e32 v4, 0x42800000, v12
	v_cvt_pk_fp8_f32 v16, v0, v4 op_sel:[0,0,1]
	v_mul_f32_e32 v0, 0x42800000, v9
	v_mul_f32_e32 v1, 0x42800000, v13
	v_cvt_pk_fp8_f32 v8, v0, v1 op_sel:[0,0,1]
	v_mul_f32_e32 v0, 0x42800000, v2
	v_mul_f32_e32 v1, 0x42800000, v6
	v_mov_b32_e32 v2, v213
	v_cvt_pk_fp8_f32 v2, v0, v1
	v_mul_f32_e32 v3, 0x42800000, v3
	v_mul_f32_e32 v4, 0x42800000, v7
	v_mov_b32_e32 v5, v213
	v_cvt_pk_fp8_f32 v5, v3, v4
	v_mul_f32_e32 v0, 0x42800000, v10
	v_mul_f32_e32 v1, 0x42800000, v14
	v_cvt_pk_fp8_f32 v2, v0, v1 op_sel:[0,0,1]
	v_mul_f32_e32 v0, 0x42800000, v11
	v_mul_f32_e32 v1, 0x42800000, v15
	v_cvt_pk_fp8_f32 v5, v0, v1 op_sel:[0,0,1]
	v_add_u32_e32 v0, 0x1c70, v48
	ds_write2_b32 v0, v16, v8 offset1:1
	v_add_u32_e32 v0, 0x1c78, v48
	ds_write2_b32 v0, v2, v5 offset1:1
	v_and_b32_e32 v0, 7, v88
	v_lshrrev_b32_e32 v14, 3, v89
	v_mul_u32_u24_e32 v1, 0x410, v0
	v_lshlrev_b32_e32 v212, 4, v0
	v_lshlrev_b32_e32 v0, 2, v14
	s_waitcnt lgkmcnt(0)
	v_add3_u32 v18, s89, v1, v0
	ds_read2_b32 v[8:9], v18 offset1:8
	ds_read2_b32 v[0:1], v18 offset0:65 offset1:73
	ds_read2_b32 v[10:11], v18 offset0:130 offset1:138
	ds_read2_b32 v[2:3], v18 offset0:195 offset1:203
	v_or_b32_e32 v14, s4, v14
	v_lshl_add_u64 v[4:5], s[22:23], 0, v[212:213]
	v_ashrrev_i32_e32 v15, 31, v14
	v_lshl_add_u64 v[12:13], v[4:5], 0, s[20:21]
	v_lshlrev_b64 v[16:17], 10, v[14:15]
	s_waitcnt lgkmcnt(3)
	v_mov_b32_e32 v4, v8
	s_waitcnt lgkmcnt(2)
	v_mov_b32_e32 v5, v0
	s_waitcnt lgkmcnt(1)
	v_mov_b32_e32 v6, v10
	s_waitcnt lgkmcnt(0)
	v_mov_b32_e32 v7, v2
	v_lshl_add_u64 v[16:17], v[12:13], 0, v[16:17]
	global_store_dwordx4 v[16:17], v[4:7], off nt
	v_mov_b32_e32 v0, v9
	v_mov_b32_e32 v2, v11
	v_or_b32_e32 v4, 8, v14
	v_ashrrev_i32_e32 v5, 31, v4
	v_lshlrev_b64 v[4:5], 10, v[4:5]
	v_lshl_add_u64 v[8:9], v[12:13], 0, v[4:5]
	ds_read2_b32 v[10:11], v18 offset0:16 offset1:24
	ds_read2_b32 v[4:5], v18 offset0:81 offset1:89
	ds_read2_b32 v[16:17], v18 offset0:146 offset1:154
	ds_read2_b32 v[6:7], v18 offset0:211 offset1:219
	global_store_dwordx4 v[8:9], v[0:3], off nt
	v_or_b32_e32 v8, 16, v14
	v_ashrrev_i32_e32 v9, 31, v8
	v_lshlrev_b64 v[8:9], 10, v[8:9]
	s_waitcnt lgkmcnt(3)
	v_mov_b32_e32 v0, v10
	s_waitcnt lgkmcnt(2)
	v_mov_b32_e32 v1, v4
	s_waitcnt lgkmcnt(1)
	v_mov_b32_e32 v2, v16
	s_waitcnt lgkmcnt(0)
	v_mov_b32_e32 v3, v6
	v_lshl_add_u64 v[8:9], v[12:13], 0, v[8:9]
	global_store_dwordx4 v[8:9], v[0:3], off nt
	v_mov_b32_e32 v4, v11
	v_mov_b32_e32 v6, v17
	v_or_b32_e32 v0, 24, v14
	v_ashrrev_i32_e32 v1, 31, v0
	v_lshlrev_b64 v[0:1], 10, v[0:1]
	v_lshl_add_u64 v[8:9], v[12:13], 0, v[0:1]
	ds_read2_b32 v[10:11], v18 offset0:32 offset1:40
	ds_read2_b32 v[0:1], v18 offset0:97 offset1:105
	ds_read2_b32 v[16:17], v18 offset0:162 offset1:170
	ds_read2_b32 v[2:3], v18 offset0:227 offset1:235
	global_store_dwordx4 v[8:9], v[4:7], off nt
	v_or_b32_e32 v8, 32, v14
	v_ashrrev_i32_e32 v9, 31, v8
	v_lshlrev_b64 v[8:9], 10, v[8:9]
	s_waitcnt lgkmcnt(3)
	v_mov_b32_e32 v4, v10
	s_waitcnt lgkmcnt(2)
	v_mov_b32_e32 v5, v0
	s_waitcnt lgkmcnt(1)
	v_mov_b32_e32 v6, v16
	s_waitcnt lgkmcnt(0)
	v_mov_b32_e32 v7, v2
	v_lshl_add_u64 v[8:9], v[12:13], 0, v[8:9]
	global_store_dwordx4 v[8:9], v[4:7], off nt
	v_mov_b32_e32 v0, v11
	v_mov_b32_e32 v2, v17
	v_or_b32_e32 v4, 40, v14
	v_ashrrev_i32_e32 v5, 31, v4
	v_lshlrev_b64 v[4:5], 10, v[4:5]
	v_lshl_add_u64 v[8:9], v[12:13], 0, v[4:5]
	ds_read2_b32 v[10:11], v18 offset0:48 offset1:56
	ds_read2_b32 v[4:5], v18 offset0:113 offset1:121
	ds_read2_b32 v[16:17], v18 offset0:178 offset1:186
	ds_read2_b32 v[6:7], v18 offset0:243 offset1:251
	global_store_dwordx4 v[8:9], v[0:3], off nt
	v_or_b32_e32 v8, 48, v14
	v_ashrrev_i32_e32 v9, 31, v8
	v_lshlrev_b64 v[8:9], 10, v[8:9]
	s_waitcnt lgkmcnt(3)
	v_mov_b32_e32 v0, v10
	s_waitcnt lgkmcnt(2)
	v_mov_b32_e32 v1, v4
	s_waitcnt lgkmcnt(1)
	v_mov_b32_e32 v2, v16
	s_waitcnt lgkmcnt(0)
	v_mov_b32_e32 v3, v6
	v_lshl_add_u64 v[8:9], v[12:13], 0, v[8:9]
	global_store_dwordx4 v[8:9], v[0:3], off nt
	v_mov_b32_e32 v4, v11
	v_mov_b32_e32 v6, v17
	v_or_b32_e32 v0, 56, v14
	v_ashrrev_i32_e32 v1, 31, v0
	v_lshlrev_b64 v[0:1], 10, v[0:1]
	v_lshl_add_u64 v[0:1], v[12:13], 0, v[0:1]
	global_store_dwordx4 v[0:1], v[4:7], off nt
	s_waitcnt lgkmcnt(0)

.LBB0_395:
	s_andn2_b64 vcc, exec, s[4:5]
	s_cbranch_vccnz .LBB0_429
	s_mov_b64 s[4:5], s[0:1]
	s_ashr_i32 s15, s14, 8
	s_load_dwordx2 s[4:5], s[4:5], 0x70
	s_ashr_i32 s21, s15, 31
	s_add_u32 s20, s15, s90
	s_addc_u32 s21, s21, 0
	s_lshl_b64 s[22:23], s[20:21], 23
	s_waitcnt lgkmcnt(0)
	s_add_u32 s24, s4, s22
	s_addc_u32 s23, s5, s23
	s_bfe_u32 s22, s14, 0x30005
	s_lshl_b32 s5, s14, 6
	s_lshl_b32 s4, s22, 11
	s_and_b32 s5, s5, 0x3fc0
	s_sub_i32 s4, s5, s4
	s_ashr_i32 s5, s4, 31
	s_lshl_b64 s[14:15], s[4:5], 2
	s_add_u32 s14, s24, s14
	v_lshlrev_b32_e32 v0, 4, v89
	v_lshrrev_b32_e32 v130, 4, v89
	s_addc_u32 s15, s23, s15
	v_and_b32_e32 v212, 0xf0, v0
	s_lshl_b32 s5, s22, 20
	v_lshl_add_u64 v[0:1], s[14:15], 0, v[212:213]
	v_lshl_or_b32 v2, v130, 15, s5
	v_mov_b32_e32 v3, v213
	v_lshl_add_u64 v[8:9], v[0:1], 0, v[2:3]
	v_add_co_u32_e32 v0, vcc, s35, v8
	s_movk_i32 s5, 0x4000
	s_nop 0
	v_addc_co_u32_e32 v1, vcc, 0, v9, vcc
	global_load_dwordx4 v[90:93], v[8:9], off nt
	global_load_dwordx4 v[94:97], v[0:1], off nt
	v_add_co_u32_e32 v0, vcc, s5, v8
	s_mov_b32 s5, 0x24000
	s_nop 1
	v_addc_co_u32_e32 v1, vcc, 0, v9, vcc
	v_add_co_u32_e32 v2, vcc, s37, v8
	s_nop 1
	v_addc_co_u32_e32 v3, vcc, 0, v9, vcc
	global_load_dwordx4 v[98:101], v[0:1], off nt
	global_load_dwordx4 v[102:105], v[2:3], off nt
	v_add_co_u32_e32 v0, vcc, s77, v8
	s_nop 1
	v_addc_co_u32_e32 v1, vcc, 0, v9, vcc
	v_add_co_u32_e32 v2, vcc, s31, v8
	s_nop 1
	v_addc_co_u32_e32 v3, vcc, 0, v9, vcc
	global_load_dwordx4 v[106:109], v[0:1], off nt
	global_load_dwordx4 v[110:113], v[2:3], off nt
	v_add_co_u32_e32 v0, vcc, s5, v8
	s_mov_b32 s5, 0x26000
	s_nop 1
	v_addc_co_u32_e32 v1, vcc, 0, v9, vcc
	v_add_co_u32_e32 v2, vcc, s5, v8
	s_mov_b32 s5, 0x42000
	s_nop 1
	v_addc_co_u32_e32 v3, vcc, 0, v9, vcc
	global_load_dwordx4 v[114:117], v[0:1], off nt
	global_load_dwordx4 v[118:121], v[2:3], off nt
	v_add_co_u32_e32 v0, vcc, s36, v8
	s_nop 1
	v_addc_co_u32_e32 v1, vcc, 0, v9, vcc
	v_add_co_u32_e32 v2, vcc, s5, v8
	s_mov_b32 s5, 0x44000
	s_nop 1
	v_addc_co_u32_e32 v3, vcc, 0, v9, vcc
	global_load_dwordx4 v[80:83], v[0:1], off nt
	global_load_dwordx4 v[84:87], v[2:3], off nt
	v_add_co_u32_e32 v0, vcc, s5, v8
	s_mov_b32 s5, 0x46000
	s_nop 1
	v_addc_co_u32_e32 v1, vcc, 0, v9, vcc
	v_add_co_u32_e32 v2, vcc, s5, v8
	s_mov_b32 s5, 0x60000
	s_nop 1
	v_addc_co_u32_e32 v3, vcc, 0, v9, vcc
	global_load_dwordx4 v[122:125], v[0:1], off nt
	global_load_dwordx4 v[126:129], v[2:3], off nt
	v_add_co_u32_e32 v0, vcc, s5, v8
	s_mov_b32 s5, 0x62000
	s_nop 1
	v_addc_co_u32_e32 v1, vcc, 0, v9, vcc
	v_add_co_u32_e32 v2, vcc, s5, v8
	s_mov_b32 s5, 0x64000
	s_nop 1
	v_addc_co_u32_e32 v3, vcc, 0, v9, vcc
	global_load_dwordx4 v[64:67], v[0:1], off nt
	global_load_dwordx4 v[68:71], v[2:3], off nt
	v_add_co_u32_e32 v0, vcc, s5, v8
	s_mov_b32 s5, 0x66000
	s_nop 1
	v_addc_co_u32_e32 v1, vcc, 0, v9, vcc
	v_add_co_u32_e32 v2, vcc, s5, v8
	s_mov_b32 s5, 0x80000
	s_nop 1
	v_addc_co_u32_e32 v3, vcc, 0, v9, vcc
	global_load_dwordx4 v[72:75], v[0:1], off nt
	global_load_dwordx4 v[76:79], v[2:3], off nt
	v_add_co_u32_e32 v0, vcc, s5, v8
	s_mov_b32 s5, 0x82000
	s_nop 1
	v_addc_co_u32_e32 v1, vcc, 0, v9, vcc
	v_add_co_u32_e32 v2, vcc, s5, v8
	s_mov_b32 s5, 0x84000
	s_nop 1
	v_addc_co_u32_e32 v3, vcc, 0, v9, vcc
	global_load_dwordx4 v[48:51], v[0:1], off nt
	global_load_dwordx4 v[52:55], v[2:3], off nt
	v_add_co_u32_e32 v0, vcc, s5, v8
	s_mov_b32 s5, 0x86000
	s_nop 1
	v_addc_co_u32_e32 v1, vcc, 0, v9, vcc
	v_add_co_u32_e32 v2, vcc, s5, v8
	s_mov_b32 s5, 0xa0000
	s_nop 1
	v_addc_co_u32_e32 v3, vcc, 0, v9, vcc
	global_load_dwordx4 v[56:59], v[0:1], off nt
	global_load_dwordx4 v[60:63], v[2:3], off nt
	v_add_co_u32_e32 v0, vcc, s5, v8
	s_mov_b32 s5, 0xa2000
	s_nop 1
	v_addc_co_u32_e32 v1, vcc, 0, v9, vcc
	v_add_co_u32_e32 v2, vcc, s5, v8
	s_mov_b32 s5, 0xa4000
	s_nop 1
	v_addc_co_u32_e32 v3, vcc, 0, v9, vcc
	global_load_dwordx4 v[32:35], v[0:1], off nt
	global_load_dwordx4 v[36:39], v[2:3], off nt
	v_add_co_u32_e32 v0, vcc, s5, v8
	s_mov_b32 s5, 0xa6000
	s_nop 1
	v_addc_co_u32_e32 v1, vcc, 0, v9, vcc
	v_add_co_u32_e32 v2, vcc, s5, v8
	s_mov_b32 s5, 0xc0000
	s_nop 1
	v_addc_co_u32_e32 v3, vcc, 0, v9, vcc
	global_load_dwordx4 v[40:43], v[0:1], off nt
	global_load_dwordx4 v[44:47], v[2:3], off nt
	v_add_co_u32_e32 v0, vcc, s5, v8
	s_mov_b32 s5, 0xc2000
	s_nop 1
	v_addc_co_u32_e32 v1, vcc, 0, v9, vcc
	v_add_co_u32_e32 v2, vcc, s5, v8
	s_nop 1
	v_addc_co_u32_e32 v3, vcc, 0, v9, vcc
	s_mov_b32 s5, 0xc4000
	global_load_dwordx4 v[16:19], v[0:1], off nt
	global_load_dwordx4 v[20:23], v[2:3], off nt
	v_add_co_u32_e32 v0, vcc, s5, v8
	s_mov_b32 s5, 0xc6000
	s_nop 1
	v_addc_co_u32_e32 v1, vcc, 0, v9, vcc
	v_add_co_u32_e32 v2, vcc, s5, v8
	s_nop 1
	v_addc_co_u32_e32 v3, vcc, 0, v9, vcc
	s_mov_b32 s5, 0xe0000
	global_load_dwordx4 v[24:27], v[0:1], off nt
	global_load_dwordx4 v[28:31], v[2:3], off nt
	v_add_co_u32_e32 v0, vcc, s5, v8
	s_nop 1
	v_addc_co_u32_e32 v1, vcc, 0, v9, vcc
	s_mov_b32 s5, 0xe2000
	v_add_co_u32_e32 v4, vcc, s5, v8
	s_mov_b32 s5, 0xe4000
	s_nop 1
	v_addc_co_u32_e32 v5, vcc, 0, v9, vcc
	v_add_co_u32_e32 v10, vcc, s5, v8
	s_nop 1
	v_addc_co_u32_e32 v11, vcc, 0, v9, vcc
	s_mov_b32 s5, 0xe6000
	v_add_co_u32_e32 v12, vcc, s5, v8
	s_nop 1
	v_addc_co_u32_e32 v13, vcc, 0, v9, vcc
	global_load_dwordx4 v[0:3], v[0:1], off nt
	global_load_dwordx4 v[4:7], v[4:5], off nt
	global_load_dwordx4 v[8:11], v[10:11], off nt
	global_load_dwordx4 v[12:15], v[12:13], off nt
	s_nop 0
	v_mov_b32_e32 v131, v213
	s_nop 0
	s_waitcnt vmcnt(31)
	v_mul_f32_e32 v90, 0x42800000, v90
	s_waitcnt vmcnt(30)
	v_mul_f32_e32 v94, 0x42800000, v94
	s_nop 0
	s_nop 0
	v_cvt_pk_fp8_f32 v131, v90, v94
	s_nop 0
	s_nop 0
	s_nop 0
	s_nop 0
	s_nop 0
	s_nop 0
	s_nop 0
	s_nop 0
	s_nop 0
	s_nop 0
	s_nop 0
	s_nop 0
	s_nop 0
	s_nop 0
	s_nop 0
	s_nop 0
	s_nop 0
	s_waitcnt vmcnt(29)
	v_mul_f32_e32 v90, 0x42800000, v98
	v_mul_f32_e32 v91, 0x42800000, v91
	v_mul_f32_e32 v95, 0x42800000, v95
	v_mov_b32_e32 v98, v213
	v_cvt_pk_fp8_f32 v98, v91, v95
	s_nop 0
	s_waitcnt vmcnt(28)
	v_mul_f32_e32 v94, 0x42800000, v102
	v_cvt_pk_fp8_f32 v131, v90, v94 op_sel:[0,0,1]
	v_mul_f32_e32 v90, 0x42800000, v99
	v_mul_f32_e32 v91, 0x42800000, v103
	v_cvt_pk_fp8_f32 v98, v90, v91 op_sel:[0,0,1]
	v_mul_f32_e32 v90, 0x42800000, v92
	v_mul_f32_e32 v91, 0x42800000, v96
	v_mov_b32_e32 v92, v213
	v_cvt_pk_fp8_f32 v92, v90, v91
	v_mul_f32_e32 v93, 0x42800000, v93
	v_mul_f32_e32 v94, 0x42800000, v97
	v_mov_b32_e32 v95, v213
	v_cvt_pk_fp8_f32 v95, v93, v94
	s_nop 0
	v_mul_f32_e32 v90, 0x42800000, v100
	v_mul_f32_e32 v91, 0x42800000, v104
	v_cvt_pk_fp8_f32 v92, v90, v91 op_sel:[0,0,1]
	v_mul_f32_e32 v90, 0x42800000, v101
	v_mul_f32_e32 v91, 0x42800000, v105
	v_cvt_pk_fp8_f32 v95, v90, v91 op_sel:[0,0,1]
	v_mul_u32_u24_e32 v90, 0x104, v130
	s_nop 0
	v_add3_u32 v90, s89, v212, v90
	s_nop 0
	s_nop 0
	s_nop 0
	ds_write2_b32 v90, v131, v98 offset1:1
	ds_write2_b32 v90, v92, v95 offset0:2 offset1:3
	s_waitcnt vmcnt(27)
	v_mul_f32_e32 v91, 0x42800000, v106
	s_waitcnt vmcnt(26)
	v_mul_f32_e32 v92, 0x42800000, v110
	v_mov_b32_e32 v93, v213
	v_cvt_pk_fp8_f32 v93, v91, v92
	v_mul_f32_e32 v94, 0x42800000, v107
	v_mul_f32_e32 v95, 0x42800000, v111
	v_mov_b32_e32 v96, v213
	v_cvt_pk_fp8_f32 v96, v94, v95
	s_waitcnt vmcnt(25)
	v_mul_f32_e32 v91, 0x42800000, v114
	s_waitcnt vmcnt(24)
	v_mul_f32_e32 v92, 0x42800000, v118
	v_cvt_pk_fp8_f32 v93, v91, v92 op_sel:[0,0,1]
	v_mul_f32_e32 v91, 0x42800000, v115
	v_mul_f32_e32 v92, 0x42800000, v119
	v_cvt_pk_fp8_f32 v96, v91, v92 op_sel:[0,0,1]
	v_mul_f32_e32 v91, 0x42800000, v108
	v_mul_f32_e32 v92, 0x42800000, v112
	v_mov_b32_e32 v94, v213
	v_cvt_pk_fp8_f32 v94, v91, v92
	v_mul_f32_e32 v95, 0x42800000, v109
	v_mul_f32_e32 v97, 0x42800000, v113
	v_mov_b32_e32 v98, v213
	v_cvt_pk_fp8_f32 v98, v95, v97
	v_mul_f32_e32 v91, 0x42800000, v116
	v_mul_f32_e32 v92, 0x42800000, v120
	v_cvt_pk_fp8_f32 v94, v91, v92 op_sel:[0,0,1]
	v_mul_f32_e32 v91, 0x42800000, v117
	v_mul_f32_e32 v92, 0x42800000, v121
	v_cvt_pk_fp8_f32 v98, v91, v92 op_sel:[0,0,1]
	v_add_u32_e32 v91, 0x410, v90
	ds_write2_b32 v91, v93, v96 offset1:1
	v_add_u32_e32 v91, 0x418, v90
	ds_write2_b32 v91, v94, v98 offset1:1
	s_waitcnt vmcnt(23)
	v_mul_f32_e32 v80, 0x42800000, v80
	s_waitcnt vmcnt(22)
	v_mul_f32_e32 v84, 0x42800000, v84
	v_mov_b32_e32 v91, v213
	v_cvt_pk_fp8_f32 v91, v80, v84
	v_mul_f32_e32 v81, 0x42800000, v81
	v_mul_f32_e32 v85, 0x42800000, v85
	v_mov_b32_e32 v92, v213
	v_cvt_pk_fp8_f32 v92, v81, v85
	s_waitcnt vmcnt(21)
	v_mul_f32_e32 v80, 0x42800000, v122
	s_waitcnt vmcnt(20)
	v_mul_f32_e32 v84, 0x42800000, v126
	v_cvt_pk_fp8_f32 v91, v80, v84 op_sel:[0,0,1]
	v_mul_f32_e32 v80, 0x42800000, v123
	v_mul_f32_e32 v81, 0x42800000, v127
	v_cvt_pk_fp8_f32 v92, v80, v81 op_sel:[0,0,1]
	v_mul_f32_e32 v80, 0x42800000, v82
	v_mul_f32_e32 v81, 0x42800000, v86
	v_mov_b32_e32 v82, v213
	v_cvt_pk_fp8_f32 v82, v80, v81
	v_mul_f32_e32 v83, 0x42800000, v83
	v_mul_f32_e32 v84, 0x42800000, v87
	v_mov_b32_e32 v85, v213
	v_cvt_pk_fp8_f32 v85, v83, v84
	v_mul_f32_e32 v80, 0x42800000, v124
	v_mul_f32_e32 v81, 0x42800000, v128
	v_cvt_pk_fp8_f32 v82, v80, v81 op_sel:[0,0,1]
	v_mul_f32_e32 v80, 0x42800000, v125
	v_mul_f32_e32 v81, 0x42800000, v129
	v_cvt_pk_fp8_f32 v85, v80, v81 op_sel:[0,0,1]
	v_add_u32_e32 v80, 0x820, v90
	ds_write2_b32 v80, v91, v92 offset1:1
	v_add_u32_e32 v80, 0x828, v90
	ds_write2_b32 v80, v82, v85 offset1:1
	s_waitcnt vmcnt(19)
	v_mul_f32_e32 v64, 0x42800000, v64
	s_waitcnt vmcnt(18)
	v_mul_f32_e32 v68, 0x42800000, v68
	v_mov_b32_e32 v80, v213
	v_cvt_pk_fp8_f32 v80, v64, v68
	s_waitcnt vmcnt(17)
	v_mul_f32_e32 v64, 0x42800000, v72
	v_mul_f32_e32 v65, 0x42800000, v65
	v_mul_f32_e32 v69, 0x42800000, v69
	v_mov_b32_e32 v72, v213
	v_cvt_pk_fp8_f32 v72, v65, v69
	s_waitcnt vmcnt(16)
	v_mul_f32_e32 v68, 0x42800000, v76
	v_cvt_pk_fp8_f32 v80, v64, v68 op_sel:[0,0,1]
	v_mul_f32_e32 v64, 0x42800000, v73
	v_mul_f32_e32 v65, 0x42800000, v77
	v_cvt_pk_fp8_f32 v72, v64, v65 op_sel:[0,0,1]
	v_mul_f32_e32 v64, 0x42800000, v66
	v_mul_f32_e32 v65, 0x42800000, v70
	v_mov_b32_e32 v66, v213
	v_cvt_pk_fp8_f32 v66, v64, v65
	v_mul_f32_e32 v67, 0x42800000, v67
	v_mul_f32_e32 v68, 0x42800000, v71
	v_mov_b32_e32 v69, v213
	v_cvt_pk_fp8_f32 v69, v67, v68
	v_mul_f32_e32 v64, 0x42800000, v74
	v_mul_f32_e32 v65, 0x42800000, v78
	v_cvt_pk_fp8_f32 v66, v64, v65 op_sel:[0,0,1]
	v_mul_f32_e32 v64, 0x42800000, v75
	v_mul_f32_e32 v65, 0x42800000, v79
	v_cvt_pk_fp8_f32 v69, v64, v65 op_sel:[0,0,1]
	v_add_u32_e32 v64, 0xc30, v90
	ds_write2_b32 v64, v80, v72 offset1:1
	v_add_u32_e32 v64, 0xc38, v90
	ds_write2_b32 v64, v66, v69 offset1:1
	s_waitcnt vmcnt(15)
	v_mul_f32_e32 v48, 0x42800000, v48
	s_waitcnt vmcnt(14)
	v_mul_f32_e32 v52, 0x42800000, v52
	v_mov_b32_e32 v64, v213
	v_cvt_pk_fp8_f32 v64, v48, v52
	s_waitcnt vmcnt(13)
	v_mul_f32_e32 v48, 0x42800000, v56
	v_mul_f32_e32 v49, 0x42800000, v49
	v_mul_f32_e32 v53, 0x42800000, v53
	v_mov_b32_e32 v56, v213
	v_cvt_pk_fp8_f32 v56, v49, v53
	s_waitcnt vmcnt(12)
	v_mul_f32_e32 v52, 0x42800000, v60
	v_cvt_pk_fp8_f32 v64, v48, v52 op_sel:[0,0,1]
	v_mul_f32_e32 v48, 0x42800000, v57
	v_mul_f32_e32 v49, 0x42800000, v61
	v_cvt_pk_fp8_f32 v56, v48, v49 op_sel:[0,0,1]
	v_mul_f32_e32 v48, 0x42800000, v50
	v_mul_f32_e32 v49, 0x42800000, v54
	v_mov_b32_e32 v50, v213
	v_cvt_pk_fp8_f32 v50, v48, v49
	v_mul_f32_e32 v51, 0x42800000, v51
	v_mul_f32_e32 v52, 0x42800000, v55
	v_mov_b32_e32 v53, v213
	v_cvt_pk_fp8_f32 v53, v51, v52
	v_mul_f32_e32 v48, 0x42800000, v58
	v_mul_f32_e32 v49, 0x42800000, v62
	v_cvt_pk_fp8_f32 v50, v48, v49 op_sel:[0,0,1]
	v_mul_f32_e32 v48, 0x42800000, v59
	v_mul_f32_e32 v49, 0x42800000, v63
	v_cvt_pk_fp8_f32 v53, v48, v49 op_sel:[0,0,1]
	v_add_u32_e32 v48, 0x1040, v90
	ds_write2_b32 v48, v64, v56 offset1:1
	v_add_u32_e32 v48, 0x1048, v90
	ds_write2_b32 v48, v50, v53 offset1:1
	s_waitcnt vmcnt(11)
	v_mul_f32_e32 v32, 0x42800000, v32
	s_waitcnt vmcnt(10)
	v_mul_f32_e32 v36, 0x42800000, v36
	v_mov_b32_e32 v48, v213
	v_cvt_pk_fp8_f32 v48, v32, v36
	s_waitcnt vmcnt(9)
	v_mul_f32_e32 v32, 0x42800000, v40
	v_mul_f32_e32 v33, 0x42800000, v33
	v_mul_f32_e32 v37, 0x42800000, v37
	v_mov_b32_e32 v40, v213
	v_cvt_pk_fp8_f32 v40, v33, v37
	s_waitcnt vmcnt(8)
	v_mul_f32_e32 v36, 0x42800000, v44
	v_cvt_pk_fp8_f32 v48, v32, v36 op_sel:[0,0,1]
	v_mul_f32_e32 v32, 0x42800000, v41
	v_mul_f32_e32 v33, 0x42800000, v45
	v_cvt_pk_fp8_f32 v40, v32, v33 op_sel:[0,0,1]
	v_mul_f32_e32 v32, 0x42800000, v34
	v_mul_f32_e32 v33, 0x42800000, v38
	v_mov_b32_e32 v34, v213
	v_cvt_pk_fp8_f32 v34, v32, v33
	v_mul_f32_e32 v35, 0x42800000, v35
	v_mul_f32_e32 v36, 0x42800000, v39
	v_mov_b32_e32 v37, v213
	v_cvt_pk_fp8_f32 v37, v35, v36
	v_mul_f32_e32 v32, 0x42800000, v42
	v_mul_f32_e32 v33, 0x42800000, v46
	v_cvt_pk_fp8_f32 v34, v32, v33 op_sel:[0,0,1]
	v_mul_f32_e32 v32, 0x42800000, v43
	v_mul_f32_e32 v33, 0x42800000, v47
	v_cvt_pk_fp8_f32 v37, v32, v33 op_sel:[0,0,1]
	v_add_u32_e32 v32, 0x1450, v90
	ds_write2_b32 v32, v48, v40 offset1:1
	v_add_u32_e32 v32, 0x1458, v90
	ds_write2_b32 v32, v34, v37 offset1:1
	s_waitcnt vmcnt(7)
	v_mul_f32_e32 v16, 0x42800000, v16
	s_waitcnt vmcnt(6)
	v_mul_f32_e32 v20, 0x42800000, v20
	v_mov_b32_e32 v32, v213
	v_cvt_pk_fp8_f32 v32, v16, v20
	s_waitcnt vmcnt(5)
	v_mul_f32_e32 v16, 0x42800000, v24
	v_mul_f32_e32 v17, 0x42800000, v17
	v_mul_f32_e32 v21, 0x42800000, v21
	v_mov_b32_e32 v24, v213
	v_cvt_pk_fp8_f32 v24, v17, v21
	s_waitcnt vmcnt(4)
	v_mul_f32_e32 v20, 0x42800000, v28
	v_cvt_pk_fp8_f32 v32, v16, v20 op_sel:[0,0,1]
	v_mul_f32_e32 v16, 0x42800000, v25
	v_mul_f32_e32 v17, 0x42800000, v29
	v_cvt_pk_fp8_f32 v24, v16, v17 op_sel:[0,0,1]
	v_mul_f32_e32 v16, 0x42800000, v18
	v_mul_f32_e32 v17, 0x42800000, v22
	v_mov_b32_e32 v18, v213
	v_cvt_pk_fp8_f32 v18, v16, v17
	v_mul_f32_e32 v19, 0x42800000, v19
	v_mul_f32_e32 v20, 0x42800000, v23
	v_mov_b32_e32 v21, v213
	v_cvt_pk_fp8_f32 v21, v19, v20
	v_mul_f32_e32 v16, 0x42800000, v26
	v_mul_f32_e32 v17, 0x42800000, v30
	v_cvt_pk_fp8_f32 v18, v16, v17 op_sel:[0,0,1]
	v_mul_f32_e32 v16, 0x42800000, v27
	v_mul_f32_e32 v17, 0x42800000, v31
	v_cvt_pk_fp8_f32 v21, v16, v17 op_sel:[0,0,1]
	v_add_u32_e32 v16, 0x1860, v90
	ds_write2_b32 v16, v32, v24 offset1:1
	v_add_u32_e32 v16, 0x1868, v90
	ds_write2_b32 v16, v18, v21 offset1:1
	s_waitcnt vmcnt(3)
	v_mul_f32_e32 v0, 0x42800000, v0
	s_waitcnt vmcnt(2)
	v_mul_f32_e32 v4, 0x42800000, v4
	v_mov_b32_e32 v16, v213
	v_cvt_pk_fp8_f32 v16, v0, v4
	s_waitcnt vmcnt(1)
	v_mul_f32_e32 v0, 0x42800000, v8
	v_mul_f32_e32 v1, 0x42800000, v1
	v_mul_f32_e32 v5, 0x42800000, v5
	v_mov_b32_e32 v8, v213
	v_cvt_pk_fp8_f32 v8, v1, v5
	s_waitcnt vmcnt(0)
	v_mul_f32_e32 v4, 0x42800000, v12
	v_cvt_pk_fp8_f32 v16, v0, v4 op_sel:[0,0,1]
	v_mul_f32_e32 v0, 0x42800000, v9
	v_mul_f32_e32 v1, 0x42800000, v13
	v_cvt_pk_fp8_f32 v8, v0, v1 op_sel:[0,0,1]
	v_mul_f32_e32 v0, 0x42800000, v2
	v_mul_f32_e32 v1, 0x42800000, v6
	v_mov_b32_e32 v2, v213
	v_cvt_pk_fp8_f32 v2, v0, v1
	v_mul_f32_e32 v3, 0x42800000, v3
	v_mul_f32_e32 v4, 0x42800000, v7
	v_mov_b32_e32 v5, v213
	v_cvt_pk_fp8_f32 v5, v3, v4
	v_mul_f32_e32 v0, 0x42800000, v10
	v_mul_f32_e32 v1, 0x42800000, v14
	v_cvt_pk_fp8_f32 v2, v0, v1 op_sel:[0,0,1]
	v_mul_f32_e32 v0, 0x42800000, v11
	v_mul_f32_e32 v1, 0x42800000, v15
	v_cvt_pk_fp8_f32 v5, v0, v1 op_sel:[0,0,1]
	v_add_u32_e32 v0, 0x1c70, v90
	ds_write2_b32 v0, v16, v8 offset1:1
	v_add_u32_e32 v0, 0x1c78, v90
	v_and_b32_e32 v4, 7, v88
	v_lshrrev_b32_e32 v8, 3, v89
	ds_write2_b32 v0, v2, v5 offset1:1
	v_mul_u32_u24_e32 v0, 0x410, v4
	v_lshlrev_b32_e32 v1, 2, v8
	s_waitcnt lgkmcnt(0)
	v_add3_u32 v9, s89, v0, v1
	ds_read2_b32 v[0:1], v9 offset1:65
	ds_read2_b32 v[2:3], v9 offset0:130 offset1:195
	v_or_b32_e32 v5, s4, v8
	s_movk_i32 s5, 0x3ff
	v_cmp_lt_i32_e32 vcc, s5, v5
	v_lshlrev_b32_e32 v7, 1, v5
	v_and_b32_e32 v5, 0x47, v5
	s_and_saveexec_b64 s[14:15], vcc
	s_xor_b64 s[14:15], exec, s[14:15]
	v_add_u32_e32 v6, 0x7ffff800, v7
	v_and_b32_e32 v6, 0x7fffff00, v6
	s_movk_i32 s5, 0x80
	v_or3_b32 v6, v5, v6, s5
	s_andn2_saveexec_b64 s[14:15], s[14:15]
	s_movk_i32 s5, 0xff00
	v_and_or_b32 v6, v7, s5, v5
	s_or_b64 exec, exec, s[14:15]
	s_lshl_b64 s[14:15], s[20:21], 21
	s_add_u32 s2, s2, s14
	s_addc_u32 s3, s3, s15
	s_lshl_b32 s5, s22, 7
	s_add_u32 s2, s2, s5
	v_lshlrev_b32_e32 v212, 4, v4
	s_addc_u32 s3, s3, 0
	v_lshl_add_u64 v[4:5], s[2:3], 0, v[212:213]
	s_mov_b64 s[2:3], 0x4000000
	v_ashrrev_i32_e32 v7, 31, v6
	v_lshl_add_u64 v[4:5], v[4:5], 0, s[2:3]
	v_lshlrev_b64 v[6:7], 10, v[6:7]
	v_lshl_add_u64 v[6:7], v[4:5], 0, v[6:7]
	s_waitcnt lgkmcnt(0)
	global_store_dwordx4 v[6:7], v[0:3], off nt
	ds_read2_b32 v[0:1], v9 offset0:8 offset1:73
	ds_read2_b32 v[2:3], v9 offset0:138 offset1:203
	v_or3_b32 v6, v8, s4, 8
	s_movk_i32 s2, 0x3ff
	v_cmp_lt_i32_e32 vcc, s2, v6
	v_lshlrev_b32_e32 v10, 1, v6
	v_and_b32_e32 v7, 0x4f, v6
	s_and_saveexec_b64 s[2:3], vcc
	s_xor_b64 s[2:3], exec, s[2:3]
	v_add_u32_e32 v6, 0x7ffff800, v10
	v_and_b32_e32 v6, 0x7fffff00, v6
	s_movk_i32 s5, 0x80
	v_or3_b32 v6, v7, v6, s5
	s_andn2_saveexec_b64 s[2:3], s[2:3]
	s_movk_i32 s5, 0xff00
	v_and_or_b32 v6, v10, s5, v7
	s_or_b64 exec, exec, s[2:3]
	v_ashrrev_i32_e32 v7, 31, v6
	v_lshlrev_b64 v[6:7], 10, v[6:7]
	v_lshl_add_u64 v[6:7], v[4:5], 0, v[6:7]
	s_waitcnt lgkmcnt(0)
	global_store_dwordx4 v[6:7], v[0:3], off nt
	ds_read2_b32 v[0:1], v9 offset0:16 offset1:81
	ds_read2_b32 v[2:3], v9 offset0:146 offset1:211
	v_or3_b32 v6, v8, s4, 16
	s_movk_i32 s2, 0x3ff
	v_cmp_lt_i32_e32 vcc, s2, v6
	v_lshlrev_b32_e32 v10, 1, v6
	v_and_b32_e32 v7, 0x57, v6
	s_and_saveexec_b64 s[2:3], vcc
	s_xor_b64 s[2:3], exec, s[2:3]
	v_add_u32_e32 v6, 0x7ffff800, v10
	v_and_b32_e32 v6, 0x7fffff00, v6
	s_movk_i32 s5, 0x80
	v_or3_b32 v6, v7, v6, s5
	s_andn2_saveexec_b64 s[2:3], s[2:3]
	s_movk_i32 s5, 0xff00
	v_and_or_b32 v6, v10, s5, v7
	s_or_b64 exec, exec, s[2:3]
	v_ashrrev_i32_e32 v7, 31, v6
	v_lshlrev_b64 v[6:7], 10, v[6:7]
	v_lshl_add_u64 v[6:7], v[4:5], 0, v[6:7]
	s_waitcnt lgkmcnt(0)
	global_store_dwordx4 v[6:7], v[0:3], off nt
	ds_read2_b32 v[0:1], v9 offset0:24 offset1:89
	ds_read2_b32 v[2:3], v9 offset0:154 offset1:219
	v_or3_b32 v6, v8, s4, 24
	s_movk_i32 s2, 0x3ff
	v_cmp_lt_i32_e32 vcc, s2, v6
	v_lshlrev_b32_e32 v10, 1, v6
	v_and_b32_e32 v7, 0x5f, v6
	s_and_saveexec_b64 s[2:3], vcc
	s_xor_b64 s[2:3], exec, s[2:3]
	v_add_u32_e32 v6, 0x7ffff800, v10
	v_and_b32_e32 v6, 0x7fffff00, v6
	s_movk_i32 s5, 0x80
	v_or3_b32 v6, v7, v6, s5
	s_andn2_saveexec_b64 s[2:3], s[2:3]
	s_movk_i32 s5, 0xff00
	v_and_or_b32 v6, v10, s5, v7
	s_or_b64 exec, exec, s[2:3]
	v_ashrrev_i32_e32 v7, 31, v6
	v_lshlrev_b64 v[6:7], 10, v[6:7]
	v_lshl_add_u64 v[6:7], v[4:5], 0, v[6:7]
	s_waitcnt lgkmcnt(0)
	global_store_dwordx4 v[6:7], v[0:3], off nt
	ds_read2_b32 v[0:1], v9 offset0:32 offset1:97
	ds_read2_b32 v[2:3], v9 offset0:162 offset1:227
	v_or3_b32 v6, v8, s4, 32
	s_movk_i32 s2, 0x3ff
	v_cmp_lt_i32_e32 vcc, s2, v6
	v_lshlrev_b32_e32 v10, 1, v6
	v_and_b32_e32 v7, 0x67, v6
	s_and_saveexec_b64 s[2:3], vcc
	s_xor_b64 s[2:3], exec, s[2:3]
	v_add_u32_e32 v6, 0x7ffff800, v10
	v_and_b32_e32 v6, 0x7fffff00, v6
	s_movk_i32 s5, 0x80
	v_or3_b32 v6, v7, v6, s5
	s_andn2_saveexec_b64 s[2:3], s[2:3]
	s_movk_i32 s5, 0xff00
	v_and_or_b32 v6, v10, s5, v7
	s_or_b64 exec, exec, s[2:3]
	v_ashrrev_i32_e32 v7, 31, v6
	v_lshlrev_b64 v[6:7], 10, v[6:7]
	v_lshl_add_u64 v[6:7], v[4:5], 0, v[6:7]
	s_waitcnt lgkmcnt(0)
	global_store_dwordx4 v[6:7], v[0:3], off nt
	ds_read2_b32 v[0:1], v9 offset0:40 offset1:105
	ds_read2_b32 v[2:3], v9 offset0:170 offset1:235
	v_or3_b32 v6, v8, s4, 40
	s_movk_i32 s2, 0x3ff
	v_cmp_lt_i32_e32 vcc, s2, v6
	v_lshlrev_b32_e32 v10, 1, v6
	v_and_b32_e32 v7, 0x6f, v6
	s_and_saveexec_b64 s[2:3], vcc
	s_xor_b64 s[2:3], exec, s[2:3]
	v_add_u32_e32 v6, 0x7ffff800, v10
	v_and_b32_e32 v6, 0x7fffff00, v6
	s_movk_i32 s5, 0x80
	v_or3_b32 v6, v7, v6, s5
	s_andn2_saveexec_b64 s[2:3], s[2:3]
	s_movk_i32 s5, 0xff00
	v_and_or_b32 v6, v10, s5, v7
	s_or_b64 exec, exec, s[2:3]
	v_ashrrev_i32_e32 v7, 31, v6
	v_lshlrev_b64 v[6:7], 10, v[6:7]
	v_lshl_add_u64 v[6:7], v[4:5], 0, v[6:7]
	s_waitcnt lgkmcnt(0)
	global_store_dwordx4 v[6:7], v[0:3], off nt
	ds_read2_b32 v[0:1], v9 offset0:48 offset1:113
	ds_read2_b32 v[2:3], v9 offset0:178 offset1:243
	v_or3_b32 v6, v8, s4, 48
	s_movk_i32 s2, 0x3ff
	v_cmp_lt_i32_e32 vcc, s2, v6
	v_lshlrev_b32_e32 v10, 1, v6
	v_and_b32_e32 v7, 0x77, v6
	s_and_saveexec_b64 s[2:3], vcc
	s_xor_b64 s[2:3], exec, s[2:3]
	v_add_u32_e32 v6, 0x7ffff800, v10
	v_and_b32_e32 v6, 0x7fffff00, v6
	s_movk_i32 s5, 0x80
	v_or3_b32 v6, v7, v6, s5
	s_andn2_saveexec_b64 s[2:3], s[2:3]
	s_movk_i32 s5, 0xff00
	v_and_or_b32 v6, v10, s5, v7
	s_or_b64 exec, exec, s[2:3]
	v_ashrrev_i32_e32 v7, 31, v6
	v_lshlrev_b64 v[6:7], 10, v[6:7]
	v_lshl_add_u64 v[6:7], v[4:5], 0, v[6:7]
	s_waitcnt lgkmcnt(0)
	global_store_dwordx4 v[6:7], v[0:3], off nt
	ds_read2_b32 v[0:1], v9 offset0:56 offset1:121
	ds_read2_b32 v[2:3], v9 offset0:186 offset1:251
	v_or3_b32 v6, v8, s4, 56
	s_movk_i32 s2, 0x3ff
	v_cmp_lt_i32_e32 vcc, s2, v6
	v_lshlrev_b32_e32 v8, 1, v6
	v_and_b32_e32 v7, 0x7f, v6
	s_and_saveexec_b64 s[2:3], vcc
	s_xor_b64 s[2:3], exec, s[2:3]
	v_add_u32_e32 v6, 0x7ffff800, v8
	v_and_b32_e32 v6, 0x7fffff00, v6
	s_movk_i32 s4, 0x80
	v_or3_b32 v6, v7, v6, s4
	s_andn2_saveexec_b64 s[2:3], s[2:3]
	s_movk_i32 s4, 0xff00
	v_and_or_b32 v6, v8, s4, v7
	s_or_b64 exec, exec, s[2:3]
	v_ashrrev_i32_e32 v7, 31, v6
	v_lshlrev_b64 v[6:7], 10, v[6:7]
	v_lshl_add_u64 v[4:5], v[4:5], 0, v[6:7]
	s_waitcnt lgkmcnt(0)
	global_store_dwordx4 v[4:5], v[0:3], off nt
	s_waitcnt lgkmcnt(0)
